# deferred transpose hooks in the QKV and MoE up-projection phases claim 10 units (was 8)
# speedup vs baseline: 1.0076x; 1.0076x over previous
; __device__ __forceinline__ int get_bid() { int b = blockIdx.x; asm volatile("" : "+s"(b)); return b; }
; __device__ __forceinline__ void deferred_work(const Params& P, LAS unsigned char* lds, int maxclaims, int units, int limit_items) {
;     ...
;     for (int n = 0; n < maxclaims; ++n) {
;         __syncthreads();
;         if (tid == 0) { int c = -1; const unsigned cur = __hip_atomic_load(ctr, __ATOMIC_RELAXED, __HIP_MEMORY_SCOPE_AGENT);
;             const int stop = limit_items > 0 ? limit_items : TR_DEF;
;             if ((int)cur * DCH < stop) c = (int)atomicAdd(ctr, (unsigned)units);
;             *sc = c; }
;         __syncthreads();
; __global__ void __launch_bounds__(NTHR, 2) mega_fwd(Params P) {
;     ...
;                 if (DEFER && DEFER_HOOKS && rep == 0 && ph == 15) { const int rem = (S.T * S.nN) % (int)gridDim.x; if (rem != 0 && get_bid() >= rem) deferred_work(P, lds, 1, 3, 0); } } break;
.LBB0_520:
	v_readlane_b32 s0, v253, 22
	v_readlane_b32 s1, v253, 23
	v_readlane_b32 s52, v253, 11
	v_readlane_b32 s70, v253, 15
	v_readlane_b32 s60, v253, 19
	s_andn2_b64 vcc, exec, s[0:1]
	v_readlane_b32 s83, v253, 4
	v_readlane_b32 s84, v253, 5
	v_readlane_b32 s53, v253, 12
	v_readlane_b32 s71, v253, 16
	v_readlane_b32 s61, v253, 20
	s_mov_b32 s95, 0x92492493
	s_movk_i32 s48, 0x7000
	s_cbranch_vccnz .LBB0_561
	s_waitcnt lgkmcnt(0)
	s_abs_i32 s0, s79
	v_cvt_f32_u32_e32 v0, s0
	s_sub_i32 s3, 0, s0
	s_abs_i32 s2, s78
	s_ashr_i32 s1, s78, 31
	v_rcp_iflag_f32_e32 v0, v0
	s_nop 0
	v_mul_f32_e32 v0, 0x4f7ffffe, v0
	v_cvt_u32_f32_e32 v0, v0
	s_nop 0
	v_readfirstlane_b32 s4, v0
	s_mul_i32 s3, s3, s4
	s_mul_hi_u32 s3, s4, s3
	s_add_i32 s4, s4, s3
	s_mul_hi_u32 s3, s2, s4
	s_mul_i32 s3, s3, s0
	s_sub_i32 s2, s2, s3
	s_sub_i32 s3, s2, s0
	s_cmp_ge_u32 s2, s0
	s_cselect_b32 s2, s3, s2
	s_sub_i32 s3, s2, s0
	s_cmp_ge_u32 s2, s0
	s_cselect_b32 s0, s3, s2
	s_xor_b32 s0, s0, s1
	s_sub_i32 s0, s0, s1
	s_cmp_eq_u32 s0, 0
	s_cbranch_scc1 .LBB0_561
	s_mov_b32 s1, s74
	s_cmp_lt_i32 s1, s0
	s_cbranch_scc1 .LBB0_561
	v_mov_b32_e32 v14, v196
	s_waitcnt vmcnt(0)
	v_cmp_eq_u32_e32 vcc, 0, v14
	s_barrier
	s_and_saveexec_b64 s[0:1], vcc
	v_readlane_b32 s10, v253, 9
	v_readlane_b32 s11, v253, 10
	s_cbranch_execz .LBB0_529
	s_nop 3
	global_load_dword v2, v1, s[10:11] sc1
	s_movk_i32 s2, 0x179f
	v_mov_b32_e32 v0, -1
	s_waitcnt vmcnt(0)
	v_cmp_lt_i32_e32 vcc, s2, v2
	s_cbranch_vccnz .LBB0_528
	s_mov_b64 s[6:7], exec
	v_mbcnt_lo_u32_b32 v0, s6, 0
	v_mbcnt_hi_u32_b32 v0, s7, v0
	v_cmp_eq_u32_e32 vcc, 0, v0
	s_and_saveexec_b64 s[4:5], vcc
	s_cbranch_execz .LBB0_527
	s_bcnt1_i32_b64 s2, s[6:7]
	s_mul_i32 s2, s2, 10
	v_mov_b32_e32 v2, s2
	global_atomic_add v2, v1, v2, s[10:11] sc0
.LBB0_527:
	s_or_b64 exec, exec, s[4:5]
	s_waitcnt vmcnt(0)
	v_readfirstlane_b32 s2, v2
	s_nop 1
	v_mad_u32_u24 v0, v0, 10, s2

; __device__ __forceinline__ TDesc tr_decode(const Params& P, unsigned char* ws, int it, int deferred) {
;     int r = it;
;     if (deferred) {
;         if (r < TR_WI) return tr_mk(P.ffn_wi + (size_t)1024 * 7168, 1024, 7168, (bf16_t*)(ws + O_FWI) + (size_t)7168 * 1024, 1, r); r -= TR_WI;
;         if (r < TR_WO) return tr_mk(P.ffn_wo + (size_t)3584 * 1024, 3584, 1024, (bf16_t*)(ws + O_FWO) + (size_t)1024 * 3584, 0, r); r -= TR_WO;
;         if (r < 8 * TR_WI) { const int e = 8 + r / TR_WI; return tr_mk(P.moe_wi + (size_t)e * 1024 * 7168, 1024, 7168, (bf16_t*)(ws + O_MWI) + (size_t)e * 7168 * 1024, 1, r % TR_WI); } r -= 8 * TR_WI;
;         { const int e = 8 + r / TR_WO; return tr_mk(P.moe_wo + (size_t)e * 3584 * 1024, 3584, 1024, (bf16_t*)(ws + O_MWO) + (size_t)e * 1024 * 3584, 0, r % TR_WO); }
; __device__ __forceinline__ void deferred_work(const Params& P, LAS unsigned char* lds, int maxclaims, int units, int limit_items) {
;     ...
;         const int c = *sc, base = c * DCH;
;         if (c < 0 || base >= TR_DEF) break;
;         const int cend = base + units * DCH, i1 = cend < TR_DEF ? cend : TR_DEF;
;         int it = base + wave;
;         float v[32]; TDesc cur;
;         if (it < i1) { cur = tr_decode(P, ws, it, 1); tr_load(cur, v, lane); }
;         while (it < i1) {
;             const int nit = it + NWAVE; float w[32]; TDesc nx = cur;
;             if (nit < i1) { nx = tr_decode(P, ws, nit, 1); tr_load(nx, w, lane); }
.LBB0_529:
	s_or_b64 exec, exec, s[0:1]
	v_lshlrev_b32_e32 v0, 3, v14
	v_and_b32_e32 v18, 56, v0
	v_mov_b32_e32 v0, s69
	s_waitcnt lgkmcnt(0)
	s_barrier
	ds_read_b32 v0, v0
	s_movk_i32 s0, 0x179f
	v_bfe_u32 v9, v14, 5, 1
	v_and_b32_e32 v8, 63, v14
	v_mul_u32_u24_e32 v15, 0x84, v9
	s_waitcnt lgkmcnt(0)
	v_cmp_lt_u32_e32 vcc, s0, v0
	v_mul_u32_u24_e32 v10, 0x84, v18
	s_cbranch_vccnz .LBB0_560
	v_lshlrev_b32_e32 v0, 3, v0
	v_ashrrev_i32_e32 v12, 6, v14
	v_min_u32_e32 v2, 0xbcb0, v0
	v_add_u32_e32 v11, 0x50, v2
	v_add_u32_e32 v16, v0, v12
	v_cmp_lt_i32_e32 vcc, v16, v11
	s_and_saveexec_b64 s[4:5], vcc
	s_cbranch_execz .LBB0_559
	s_movk_i32 s0, 0xdff
	v_cmp_lt_i32_e32 vcc, s0, v16
	s_and_saveexec_b64 s[0:1], vcc
	s_xor_b64 s[0:1], exec, s[0:1]
	s_cbranch_execz .LBB0_541
	v_cmp_lt_u32_e32 vcc, s62, v16
	s_and_saveexec_b64 s[6:7], vcc
	s_xor_b64 s[6:7], exec, s[6:7]
	s_cbranch_execz .LBB0_538
	s_mov_b32 s2, 0x84ff
	v_cmp_lt_u32_e32 vcc, s2, v16
	s_and_saveexec_b64 s[8:9], vcc
	s_xor_b64 s[8:9], exec, s[8:9]
	s_cbranch_execz .LBB0_535
	v_add_u16_e32 v0, 0x7b00, v16
	s_movk_i32 s2, 0x2493
	v_mul_u32_u24_sdwa v13, v0, s2 dst_sel:DWORD dst_unused:UNUSED_PAD src0_sel:BYTE_1 src1_sel:DWORD
	v_add_u16_sdwa v6, v13, v201 dst_sel:DWORD dst_unused:UNUSED_PAD src0_sel:WORD_1 src1_sel:DWORD
	v_mov_b64_e32 v[2:3], s[24:25]
	s_mov_b32 s2, 0xe00000
	v_mad_u64_u32 v[2:3], s[10:11], v6, s2, v[2:3]
	v_mov_b64_e32 v[4:5], s[52:53]
	s_mov_b32 s2, 0x700000
	v_mad_u64_u32 v[6:7], s[10:11], v6, s2, v[4:5]
	s_movk_i32 s2, 0x700
	v_mul_lo_u16_sdwa v4, v13, s2 dst_sel:DWORD dst_unused:UNUSED_PAD src0_sel:WORD_1 src1_sel:DWORD
	v_sub_u16_e32 v0, v0, v4
	v_lshlrev_b16_e32 v4, 5, v0
	v_lshlrev_b16_e32 v0, 1, v0
	v_and_b32_e32 v4, 0x3e0, v4
	v_and_b32_e32 v13, 0xfc0, v0
	v_lshlrev_b32_sdwa v0, v202, v13 dst_sel:DWORD dst_unused:UNUSED_PAD src0_sel:DWORD src1_sel:WORD_0
	v_and_b32_e32 v17, 0xffff, v4
	v_lshl_add_u64 v[2:3], v[2:3], 0, v[0:1]
	v_lshlrev_b32_e32 v0, 2, v17
	s_movk_i32 s2, 0x1c00
	v_lshl_add_u64 v[4:5], v[2:3], 0, v[0:1]
	v_mad_u64_u32 v[2:3], s[10:11], v17, s2, v[6:7]
	v_lshlrev_b32_sdwa v0, v200, v13 dst_sel:DWORD dst_unused:UNUSED_PAD src0_sel:DWORD src1_sel:WORD_0
	v_lshl_add_u64 v[2:3], v[2:3], 0, v[0:1]

; __device__ __forceinline__ int get_bid() { int b = blockIdx.x; asm volatile("" : "+s"(b)); return b; }
; __device__ __forceinline__ void deferred_work(const Params& P, LAS unsigned char* lds, int maxclaims, int units, int limit_items) {
;     ...
;     for (int n = 0; n < maxclaims; ++n) {
;         __syncthreads();
;         if (tid == 0) { int c = -1; const unsigned cur = __hip_atomic_load(ctr, __ATOMIC_RELAXED, __HIP_MEMORY_SCOPE_AGENT);
;             const int stop = limit_items > 0 ? limit_items : TR_DEF;
;             if ((int)cur * DCH < stop) c = (int)atomicAdd(ctr, (unsigned)units);
;             *sc = c; }
;         __syncthreads();
; __global__ void __launch_bounds__(NTHR, 2) mega_fwd(Params P) {
;     ...
;                 if (DEFER && DEFER_HOOKS && rep == 0 && a0 == 1) { const int b = get_bid(); if (b >= 69 && !(b >= 128 && b < 193)) deferred_work(P, lds, 1, 3, 0); } } break;
.LBB0_766:
	v_readlane_b32 s0, v253, 40
	v_readlane_b32 s1, v253, 41
	s_andn2_b64 vcc, exec, s[0:1]
	s_cbranch_vccnz .LBB0_806
	s_mov_b32 s2, s74
	s_cmpk_lt_i32 s2, 0x45
	s_cselect_b64 s[0:1], -1, 0
	s_addk_i32 s2, 0xff80
	s_cmpk_lt_u32 s2, 0x41
	s_cselect_b64 s[4:5], -1, 0
	s_or_b64 s[0:1], s[0:1], s[4:5]
	s_and_b64 vcc, exec, s[0:1]
	s_cbranch_vccnz .LBB0_806
	v_mov_b32_e32 v14, v196
	s_waitcnt vmcnt(0) lgkmcnt(0)
	v_cmp_eq_u32_e32 vcc, 0, v14
	s_barrier
	s_and_saveexec_b64 s[0:1], vcc
	s_cbranch_execz .LBB0_774
	global_load_dword v2, v1, s[72:73] sc1
	s_movk_i32 s2, 0x179f
	v_mov_b32_e32 v0, -1
	s_waitcnt vmcnt(0)
	v_cmp_lt_i32_e32 vcc, s2, v2
	s_cbranch_vccnz .LBB0_773
	s_mov_b64 s[6:7], exec
	v_mbcnt_lo_u32_b32 v0, s6, 0
	v_mbcnt_hi_u32_b32 v0, s7, v0
	v_cmp_eq_u32_e32 vcc, 0, v0
	s_and_saveexec_b64 s[4:5], vcc
	s_cbranch_execz .LBB0_772
	s_bcnt1_i32_b64 s2, s[6:7]
	s_mul_i32 s2, s2, 10
	v_mov_b32_e32 v2, s2
	global_atomic_add v2, v1, v2, s[72:73] sc0
